# plus RWKV producers: wave-sum row_bcast stages fused into v_add_f32_dpp
# baseline (speedup 1.0000x reference)
.LBB0_577:
	s_and_saveexec_b64 s[0:1], s[4:5]
	s_xor_b64 s[20:21], exec, s[0:1]
	s_cbranch_execz .LBB0_595
	s_cmp_lg_u32 s18, 0
	s_cselect_b64 s[22:23], -1, 0
	s_cmp_eq_u32 s18, 0
	s_cbranch_scc1 .LBB0_580
	s_andn2_b32 s1, 1, s25
	s_lshl_b32 s0, s1, 12
	s_add_i32 s27, s0, 0
	v_lshlrev_b32_e32 v1, 2, v85
	v_add_u32_e32 v2, s27, v1
	ds_read2st64_b32 v[42:43], v2 offset0:192 offset1:224
	s_mul_i32 s0, s1, 0x5000
	s_add_i32 s26, s27, s0
	v_add_u32_e32 v1, s26, v1
	ds_read_b32 v72, v1 offset:20480
	s_waitcnt lgkmcnt(1)
	v_add_f32_dpp v2, v42, v42 quad_perm:[1,0,3,2] row_mask:0xf bank_mask:0xf bound_ctrl:1
	v_mul_f32_e32 v1, 0xbfb8aa3b, v43
	v_mov_b32_e32 v3, v0
	v_add_f32_dpp v2, v2, v2 quad_perm:[2,3,0,1] row_mask:0xf bank_mask:0xf bound_ctrl:1
	v_exp_f32_e32 v1, v1
	s_lshl_b32 s1, s1, 6
	v_add_f32_dpp v2, v2, v2 row_half_mirror row_mask:0xf bank_mask:0xf bound_ctrl:1
	s_add_i32 s1, s1, 0
	v_add_f32_e32 v1, 1.0, v1
	v_add_f32_dpp v2, v2, v2 row_mirror row_mask:0xf bank_mask:0xf bound_ctrl:1
	v_rcp_f32_e32 v74, v1
	v_lshlrev_b32_e32 v1, 2, v86
	s_nop 0
	v_add_f32_dpp v2, v2, v2 row_bcast:15 row_mask:0xa bank_mask:0xf
	s_nop 0
	s_mov_b32 s30, 0x3c800000
	v_mov_b32_e32 v36, v42
	s_nop 0
	v_add_f32_dpp v2, v2, v2 row_bcast:31 row_mask:0xc bank_mask:0xf
	s_nop 0
	v_readlane_b32 s0, v2, 63
	v_lshl_add_u32 v2, v84, 2, s1
	v_add_u32_e32 v149, 0x10000, v2
	v_add_u32_e32 v2, s27, v1
	ds_read2st64_b32 v[150:151], v2 offset0:192 offset1:224
	v_mov_b32_e32 v40, v0
	s_mov_b32 s34, 0x45800000
	v_add_u32_e32 v1, s26, v1
	ds_read_b32 v73, v1 offset:20480
	s_waitcnt lgkmcnt(1)
	v_add_f32_dpp v2, v150, v150 quad_perm:[1,0,3,2] row_mask:0xf bank_mask:0xf bound_ctrl:1
	v_mov_b32_e32 v37, v150
	v_mov_b32_e32 v150, v43
	v_add_f32_dpp v2, v2, v2 quad_perm:[2,3,0,1] row_mask:0xf bank_mask:0xf bound_ctrl:1
	s_nop 1
	v_add_f32_dpp v2, v2, v2 row_half_mirror row_mask:0xf bank_mask:0xf bound_ctrl:1
	s_nop 1
	v_add_f32_dpp v2, v2, v2 row_mirror row_mask:0xf bank_mask:0xf bound_ctrl:1
	s_nop 1
	s_nop 0
	v_add_f32_dpp v2, v2, v2 row_bcast:15 row_mask:0xa bank_mask:0xf
	s_nop 0
	s_nop 1
	s_nop 0
	v_add_f32_dpp v2, v2, v2 row_bcast:31 row_mask:0xc bank_mask:0xf
	s_nop 0
	v_readlane_b32 s1, v2, 63
	v_mov_b64_e32 v[2:3], s[30:31]
	s_mov_b32 s30, 0x3a27c5ac
	v_pk_fma_f32 v[36:37], s[0:1], v[2:3], v[36:37] op_sel_hi:[1,0,1] neg_lo:[1,0,0] neg_hi:[1,0,0]
	s_nop 0
	v_pk_mul_f32 v[38:39], v[36:37], v[36:37]
	s_nop 1
	v_add_f32_dpp v38, v38, v38 quad_perm:[1,0,3,2] row_mask:0xf bank_mask:0xf bound_ctrl:1
	s_nop 1
	v_add_f32_dpp v38, v38, v38 quad_perm:[2,3,0,1] row_mask:0xf bank_mask:0xf bound_ctrl:1
	s_nop 1
	v_add_f32_dpp v38, v38, v38 row_half_mirror row_mask:0xf bank_mask:0xf bound_ctrl:1
	s_nop 1
	v_add_f32_dpp v38, v38, v38 row_mirror row_mask:0xf bank_mask:0xf bound_ctrl:1
	s_nop 1
	s_nop 0
	v_add_f32_dpp v38, v38, v38 row_bcast:15 row_mask:0xa bank_mask:0xf
	s_nop 0
	s_nop 1
	s_nop 0
	v_add_f32_dpp v38, v38, v38 row_bcast:31 row_mask:0xc bank_mask:0xf
	v_mov_b64_e32 v[40:41], s[30:31]
	v_readlane_b32 s0, v38, 63
	v_add_f32_dpp v38, v39, v39 quad_perm:[1,0,3,2] row_mask:0xf bank_mask:0xf bound_ctrl:1
	v_mov_b32_e32 v39, v0
	s_movk_i32 s30, 0x7fff
	v_add_f32_dpp v38, v38, v38 quad_perm:[2,3,0,1] row_mask:0xf bank_mask:0xf bound_ctrl:1
	s_mov_b32 s31, 0x7060302
	s_nop 0
	v_add_f32_dpp v38, v38, v38 row_half_mirror row_mask:0xf bank_mask:0xf bound_ctrl:1
	s_nop 1
	v_add_f32_dpp v38, v38, v38 row_mirror row_mask:0xf bank_mask:0xf bound_ctrl:1
	s_nop 1
	s_nop 0
	v_add_f32_dpp v38, v38, v38 row_bcast:15 row_mask:0xa bank_mask:0xf
	s_nop 0
	s_nop 1
	s_nop 0
	v_add_f32_dpp v38, v38, v38 row_bcast:31 row_mask:0xc bank_mask:0xf
	s_nop 0
	v_readlane_b32 s1, v38, 63
	s_nop 1
	v_pk_fma_f32 v[38:39], s[0:1], v[2:3], v[40:41] op_sel_hi:[1,0,0]
	s_nop 0
	v_mul_f32_e32 v42, 0x4b800000, v38
	v_cmp_gt_f32_e64 s[0:1], s72, v38
	v_cmp_gt_f32_e32 vcc, s72, v39
	s_nop 0
	v_cndmask_b32_e64 v38, v38, v42, s[0:1]
	v_mul_f32_e32 v42, 0x4b800000, v39
	v_cndmask_b32_e32 v39, v39, v42, vcc
	v_rsq_f32_e32 v38, v38
	v_rsq_f32_e32 v39, v39
	s_nop 0
	v_pk_mul_f32 v[152:153], v[38:39], s[34:35] op_sel_hi:[1,0]
	s_nop 0
	v_cndmask_b32_e32 v39, v39, v153, vcc
	v_cndmask_b32_e64 v38, v38, v152, s[0:1]
	v_pk_mul_f32 v[36:37], v[36:37], v[38:39]
	s_nop 0
	v_pk_fma_f32 v[152:153], v[50:51], v[36:37], v[48:49]
	ds_read_b128 v[36:39], v149
	v_mul_f32_e32 v1, 0xbfb8aa3b, v151
	v_exp_f32_e32 v1, v1
	s_waitcnt lgkmcnt(0)
	v_pk_fma_f32 v[36:37], v[36:37], v[72:73], v[152:153]
	v_add_f32_e32 v1, 1.0, v1
	v_rcp_f32_e32 v75, v1
	v_mov_b32_e32 v73, v0
	v_pk_mul_f32 v[42:43], v[150:151], v[74:75]
	s_nop 0
	v_pk_mul_f32 v[36:37], v[42:43], v[36:37]
	v_mov_b32_e32 v43, v0
	v_and_b32_sdwa v1, v37, v190 dst_sel:DWORD dst_unused:UNUSED_PAD src0_sel:WORD_1 src1_sel:DWORD
	v_and_b32_sdwa v42, v36, v190 dst_sel:DWORD dst_unused:UNUSED_PAD src0_sel:WORD_1 src1_sel:DWORD
	v_add3_u32 v36, v36, v42, s30
	v_add3_u32 v1, v37, v1, s30
	v_perm_b32 v149, v1, v36, s31
	v_lshlrev_b32_e32 v1, 2, v87
	v_add_u32_e32 v36, s27, v1
	ds_read2st64_b32 v[36:37], v36 offset0:192 offset1:224
	v_add_u32_e32 v1, s26, v1
	s_waitcnt lgkmcnt(0)
	v_mov_b32_e32 v150, v36
	v_add_f32_dpp v42, v36, v36 quad_perm:[1,0,3,2] row_mask:0xf bank_mask:0xf bound_ctrl:1
	s_nop 1
	v_add_f32_dpp v42, v42, v42 quad_perm:[2,3,0,1] row_mask:0xf bank_mask:0xf bound_ctrl:1
	s_nop 1
	v_add_f32_dpp v42, v42, v42 row_half_mirror row_mask:0xf bank_mask:0xf bound_ctrl:1
	s_nop 1
	v_add_f32_dpp v42, v42, v42 row_mirror row_mask:0xf bank_mask:0xf bound_ctrl:1
	s_nop 1
	s_nop 0
	v_add_f32_dpp v42, v42, v42 row_bcast:15 row_mask:0xa bank_mask:0xf
	s_nop 0
	s_nop 1
	s_nop 0
	v_add_f32_dpp v42, v42, v42 row_bcast:31 row_mask:0xc bank_mask:0xf
	s_nop 0
	v_readlane_b32 s0, v42, 63
	ds_read_b32 v42, v1 offset:20480
	v_mul_f32_e32 v1, 0xbfb8aa3b, v37
	v_exp_f32_e32 v1, v1
	s_nop 0
	v_add_f32_e32 v1, 1.0, v1
	v_rcp_f32_e32 v72, v1
	v_lshlrev_b32_e32 v1, 2, v88
	v_add_u32_e32 v43, s27, v1
	ds_read2st64_b32 v[74:75], v43 offset0:192 offset1:224
	v_add_u32_e32 v1, s26, v1
	s_waitcnt lgkmcnt(0)
	v_mov_b32_e32 v151, v74
	v_add_f32_dpp v43, v74, v74 quad_perm:[1,0,3,2] row_mask:0xf bank_mask:0xf bound_ctrl:1
	v_mov_b32_e32 v74, v37
	s_nop 0
	v_add_f32_dpp v43, v43, v43 quad_perm:[2,3,0,1] row_mask:0xf bank_mask:0xf bound_ctrl:1
	s_nop 1
	v_add_f32_dpp v43, v43, v43 row_half_mirror row_mask:0xf bank_mask:0xf bound_ctrl:1
	s_nop 1
	v_add_f32_dpp v43, v43, v43 row_mirror row_mask:0xf bank_mask:0xf bound_ctrl:1
	s_nop 1
	s_nop 0
	v_add_f32_dpp v43, v43, v43 row_bcast:15 row_mask:0xa bank_mask:0xf
	s_nop 0
	s_nop 1
	s_nop 0
	v_add_f32_dpp v43, v43, v43 row_bcast:31 row_mask:0xc bank_mask:0xf
	s_nop 0
	v_readlane_b32 s1, v43, 63
	v_mov_b32_e32 v43, v0
	s_nop 0
	v_pk_fma_f32 v[150:151], s[0:1], v[2:3], v[150:151] op_sel_hi:[1,0,1] neg_lo:[1,0,0] neg_hi:[1,0,0]
	s_nop 0
	v_pk_mul_f32 v[152:153], v[150:151], v[150:151]
	s_nop 1
	v_add_f32_dpp v36, v152, v152 quad_perm:[1,0,3,2] row_mask:0xf bank_mask:0xf bound_ctrl:1
	s_nop 1
	v_add_f32_dpp v36, v36, v36 quad_perm:[2,3,0,1] row_mask:0xf bank_mask:0xf bound_ctrl:1
	s_nop 1
	v_add_f32_dpp v36, v36, v36 row_half_mirror row_mask:0xf bank_mask:0xf bound_ctrl:1
	s_nop 1
	v_add_f32_dpp v36, v36, v36 row_mirror row_mask:0xf bank_mask:0xf bound_ctrl:1
	s_nop 1
	s_nop 0
	v_add_f32_dpp v36, v36, v36 row_bcast:15 row_mask:0xa bank_mask:0xf
	s_nop 0
	s_nop 1
	s_nop 0
	v_add_f32_dpp v36, v36, v36 row_bcast:31 row_mask:0xc bank_mask:0xf
	s_nop 0
	v_readlane_b32 s0, v36, 63
	v_add_f32_dpp v36, v153, v153 quad_perm:[1,0,3,2] row_mask:0xf bank_mask:0xf bound_ctrl:1
	s_nop 1
	v_add_f32_dpp v36, v36, v36 quad_perm:[2,3,0,1] row_mask:0xf bank_mask:0xf bound_ctrl:1
	s_nop 1
	v_add_f32_dpp v36, v36, v36 row_half_mirror row_mask:0xf bank_mask:0xf bound_ctrl:1
	s_nop 1
	v_add_f32_dpp v36, v36, v36 row_mirror row_mask:0xf bank_mask:0xf bound_ctrl:1
	s_nop 1
	s_nop 0
	v_add_f32_dpp v36, v36, v36 row_bcast:15 row_mask:0xa bank_mask:0xf
	s_nop 0
	s_nop 1
	s_nop 0
	v_add_f32_dpp v36, v36, v36 row_bcast:31 row_mask:0xc bank_mask:0xf
	ds_read_b32 v43, v1 offset:20480
	v_readlane_b32 s1, v36, 63
	v_mul_f32_e32 v1, 0xbfb8aa3b, v75
	v_exp_f32_e32 v1, v1
	v_pk_fma_f32 v[2:3], s[0:1], v[2:3], v[40:41] op_sel_hi:[1,0,0]
	v_add_f32_e32 v1, 1.0, v1
	v_mul_f32_e32 v36, 0x4b800000, v2
	v_cmp_gt_f32_e64 s[0:1], s72, v2
	v_cmp_gt_f32_e32 vcc, s72, v3
	v_rcp_f32_e32 v73, v1
	v_cndmask_b32_e64 v2, v2, v36, s[0:1]
	v_mul_f32_e32 v36, 0x4b800000, v3
	v_cndmask_b32_e32 v3, v3, v36, vcc
	v_rsq_f32_e32 v2, v2
	v_rsq_f32_e32 v3, v3
	v_pk_mul_f32 v[36:37], v[74:75], v[72:73]
	v_pk_mul_f32 v[40:41], v[2:3], s[34:35] op_sel_hi:[1,0]
	s_nop 0
	v_cndmask_b32_e32 v3, v3, v41, vcc
	v_cndmask_b32_e64 v2, v2, v40, s[0:1]
	v_pk_mul_f32 v[2:3], v[150:151], v[2:3]
	s_nop 0
	v_pk_fma_f32 v[2:3], v[50:51], v[2:3], v[48:49]
	s_waitcnt lgkmcnt(0)
	v_pk_fma_f32 v[2:3], v[38:39], v[42:43], v[2:3]
	s_nop 0
	v_pk_mul_f32 v[2:3], v[36:37], v[2:3]
	s_nop 0
	v_and_b32_sdwa v1, v3, v190 dst_sel:DWORD dst_unused:UNUSED_PAD src0_sel:WORD_1 src1_sel:DWORD
	v_and_b32_sdwa v36, v2, v190 dst_sel:DWORD dst_unused:UNUSED_PAD src0_sel:WORD_1 src1_sel:DWORD
	v_add3_u32 v2, v2, v36, s30
	v_add3_u32 v1, v3, v1, s30
	v_perm_b32 v150, v1, v2, s31

.LBB0_624:
	s_or_b64 exec, exec, s[0:1]
	s_waitcnt lgkmcnt(0)
	s_barrier
	s_and_saveexec_b64 s[0:1], s[4:5]
	s_xor_b64 s[0:1], exec, s[0:1]
	s_cbranch_execz .LBB0_635
	s_cmp_eq_u32 s18, 0xee2000
	s_cbranch_scc1 .LBB0_635
	s_andn2_b32 s20, 1, s25
	s_mul_i32 s21, s20, 0x6000
	s_add_i32 s23, s21, 0
	v_lshl_add_u32 v1, v85, 2, s23
	ds_read2st64_b32 v[2:3], v1 offset0:16 offset1:32
	v_mov_b32_e32 v40, v0
	s_lshl_b32 s22, s20, 4
	s_waitcnt lgkmcnt(0)
	v_add_f32_e32 v2, v82, v2
	v_mul_f32_e32 v2, 0xbfb8aa3b, v2
	v_exp_f32_e32 v2, v2
	v_add_f32_e32 v3, v81, v3
	v_add_f32_e32 v2, 1.0, v2
	v_rcp_f32_e32 v2, v2
	s_nop 0
	v_mul_f32_e32 v2, 0xbf1b4598, v2
	v_mul_f32_e32 v2, 0x3fb8aa3b, v2
	v_exp_f32_e32 v36, v2
	v_mul_f32_e32 v2, 0xbfb8aa3b, v3
	v_exp_f32_e32 v2, v2
	s_nop 0
	v_add_f32_e32 v2, 1.0, v2
	v_rcp_f32_e32 v37, v2
	ds_read2st64_b32 v[2:3], v1 offset0:48 offset1:64
	s_waitcnt lgkmcnt(0)
	v_mul_f32_e32 v38, v80, v2
	v_mul_f32_e32 v39, v38, v38
	s_nop 1
	v_mov_b32_dpp v39, v39 quad_perm:[1,0,3,2] row_mask:0xf bank_mask:0xf bound_ctrl:1
	v_fmac_f32_e32 v39, v38, v38
	s_nop 1
	v_add_f32_dpp v39, v39, v39 quad_perm:[2,3,0,1] row_mask:0xf bank_mask:0xf bound_ctrl:1
	s_nop 1
	v_add_f32_dpp v39, v39, v39 row_half_mirror row_mask:0xf bank_mask:0xf bound_ctrl:1
	s_nop 1
	v_add_f32_dpp v39, v39, v39 row_mirror row_mask:0xf bank_mask:0xf bound_ctrl:1
	s_nop 1
	s_nop 0
	v_add_f32_dpp v39, v39, v39 row_bcast:15 row_mask:0xa bank_mask:0xf
	s_nop 0
	s_nop 1
	s_nop 0
	v_add_f32_dpp v39, v39, v39 row_bcast:31 row_mask:0xc bank_mask:0xf
	s_nop 0
	v_readlane_b32 s20, v39, 63
	s_nop 1
	v_add_f32_e32 v39, s20, v184
	v_cmp_gt_f32_e32 vcc, s72, v39
	v_mul_f32_e32 v40, 0x4b800000, v39
	s_nop 0
	v_cndmask_b32_e32 v39, v39, v40, vcc
	v_rsq_f32_e32 v39, v39
	s_nop 0
	v_mul_f32_e32 v40, 0x45800000, v39
	v_cndmask_b32_e32 v39, v39, v40, vcc
	v_mul_f32_e32 v38, v38, v39
	v_add_f32_e32 v39, -1.0, v37
	v_fma_f32 v39, v79, v39, 1.0
	v_mul_f32_e32 v2, v2, v39
	v_mul_f32_e32 v3, v3, v2
	v_mul_f32_e32 v39, v78, v3
	ds_write2st64_b32 v1, v38, v36 offset1:16
	s_nop 0
	v_mov_b32_dpp v39, v39 quad_perm:[1,0,3,2] row_mask:0xf bank_mask:0xf bound_ctrl:1
	v_fmac_f32_e32 v39, v78, v3
	s_nop 1
	v_add_f32_dpp v3, v39, v39 quad_perm:[2,3,0,1] row_mask:0xf bank_mask:0xf bound_ctrl:1
	v_mov_b32_e32 v39, v0
	s_nop 0
	v_add_f32_dpp v3, v3, v3 row_half_mirror row_mask:0xf bank_mask:0xf bound_ctrl:1
	s_nop 1
	v_add_f32_dpp v3, v3, v3 row_mirror row_mask:0xf bank_mask:0xf bound_ctrl:1
	s_nop 1
	s_nop 0
	v_add_f32_dpp v3, v3, v3 row_bcast:15 row_mask:0xa bank_mask:0xf
	s_nop 0
	s_nop 1
	s_nop 0
	v_add_f32_dpp v3, v3, v3 row_bcast:31 row_mask:0xc bank_mask:0xf
	s_nop 0
	v_readlane_b32 s26, v3, 63
	v_mul_f32_e32 v3, v37, v38
	ds_write2st64_b32 v1, v3, v2 offset0:32 offset1:48
	s_and_saveexec_b64 s[20:21], s[16:17]
	v_lshl_add_u32 v1, s22, 2, v106
	v_mov_b32_e32 v2, s26
	ds_write_b32 v1, v2
	s_or_b64 exec, exec, s[20:21]
	v_lshl_add_u32 v1, v86, 2, s23
	ds_read2st64_b32 v[2:3], v1 offset0:16 offset1:32
	v_mov_b32_e32 v40, v0
	s_waitcnt lgkmcnt(0)
	v_add_f32_e32 v2, v82, v2
	v_mul_f32_e32 v2, 0xbfb8aa3b, v2
	v_exp_f32_e32 v2, v2
	v_add_f32_e32 v3, v81, v3
	v_add_f32_e32 v2, 1.0, v2
	v_rcp_f32_e32 v2, v2
	s_nop 0
	v_mul_f32_e32 v2, 0xbf1b4598, v2
	v_mul_f32_e32 v2, 0x3fb8aa3b, v2
	v_exp_f32_e32 v36, v2
	v_mul_f32_e32 v2, 0xbfb8aa3b, v3
	v_exp_f32_e32 v2, v2
	s_nop 0
	v_add_f32_e32 v2, 1.0, v2
	v_rcp_f32_e32 v37, v2
	ds_read2st64_b32 v[2:3], v1 offset0:48 offset1:64
	s_waitcnt lgkmcnt(0)
	v_mul_f32_e32 v38, v80, v2
	v_mul_f32_e32 v39, v38, v38
	s_nop 1
	v_mov_b32_dpp v39, v39 quad_perm:[1,0,3,2] row_mask:0xf bank_mask:0xf bound_ctrl:1
	v_fmac_f32_e32 v39, v38, v38
	s_nop 1
	v_add_f32_dpp v39, v39, v39 quad_perm:[2,3,0,1] row_mask:0xf bank_mask:0xf bound_ctrl:1
	s_nop 1
	v_add_f32_dpp v39, v39, v39 row_half_mirror row_mask:0xf bank_mask:0xf bound_ctrl:1
	s_nop 1
	v_add_f32_dpp v39, v39, v39 row_mirror row_mask:0xf bank_mask:0xf bound_ctrl:1
	s_nop 1
	s_nop 0
	v_add_f32_dpp v39, v39, v39 row_bcast:15 row_mask:0xa bank_mask:0xf
	s_nop 0
	s_nop 1
	s_nop 0
	v_add_f32_dpp v39, v39, v39 row_bcast:31 row_mask:0xc bank_mask:0xf
	s_nop 0
	v_readlane_b32 s20, v39, 63
	s_nop 1
	v_add_f32_e32 v39, s20, v184
	v_cmp_gt_f32_e32 vcc, s72, v39
	v_mul_f32_e32 v40, 0x4b800000, v39
	s_nop 0
	v_cndmask_b32_e32 v39, v39, v40, vcc
	v_rsq_f32_e32 v39, v39
	s_nop 0
	v_mul_f32_e32 v40, 0x45800000, v39
	v_cndmask_b32_e32 v39, v39, v40, vcc
	v_mul_f32_e32 v38, v38, v39
	v_add_f32_e32 v39, -1.0, v37
	v_fma_f32 v39, v79, v39, 1.0
	v_mul_f32_e32 v2, v2, v39
	v_mul_f32_e32 v3, v3, v2
	v_mul_f32_e32 v39, v78, v3
	ds_write2st64_b32 v1, v38, v36 offset1:16
	s_nop 0
	v_mov_b32_dpp v39, v39 quad_perm:[1,0,3,2] row_mask:0xf bank_mask:0xf bound_ctrl:1
	v_fmac_f32_e32 v39, v78, v3
	s_nop 1
	v_add_f32_dpp v3, v39, v39 quad_perm:[2,3,0,1] row_mask:0xf bank_mask:0xf bound_ctrl:1
	v_mov_b32_e32 v39, v0
	s_nop 0
	v_add_f32_dpp v3, v3, v3 row_half_mirror row_mask:0xf bank_mask:0xf bound_ctrl:1
	s_nop 1
	v_add_f32_dpp v3, v3, v3 row_mirror row_mask:0xf bank_mask:0xf bound_ctrl:1
	s_nop 1
	s_nop 0
	v_add_f32_dpp v3, v3, v3 row_bcast:15 row_mask:0xa bank_mask:0xf
	s_nop 0
	s_nop 1
	s_nop 0
	v_add_f32_dpp v3, v3, v3 row_bcast:31 row_mask:0xc bank_mask:0xf
	s_nop 0
	v_readlane_b32 s26, v3, 63
	v_mul_f32_e32 v3, v37, v38
	ds_write2st64_b32 v1, v3, v2 offset0:32 offset1:48
	s_and_saveexec_b64 s[20:21], s[16:17]
	v_lshl_add_u32 v1, s22, 2, v144
	v_mov_b32_e32 v2, s26
	ds_write_b32 v1, v2
	s_or_b64 exec, exec, s[20:21]
	v_lshl_add_u32 v1, v87, 2, s23
	ds_read2st64_b32 v[2:3], v1 offset0:16 offset1:32
	v_mov_b32_e32 v40, v0
	s_waitcnt lgkmcnt(0)
	v_add_f32_e32 v2, v82, v2
	v_mul_f32_e32 v2, 0xbfb8aa3b, v2
	v_exp_f32_e32 v2, v2
	v_add_f32_e32 v3, v81, v3
	v_add_f32_e32 v2, 1.0, v2
	v_rcp_f32_e32 v2, v2
	s_nop 0
	v_mul_f32_e32 v2, 0xbf1b4598, v2
	v_mul_f32_e32 v2, 0x3fb8aa3b, v2
	v_exp_f32_e32 v36, v2
	v_mul_f32_e32 v2, 0xbfb8aa3b, v3
	v_exp_f32_e32 v2, v2
	s_nop 0
	v_add_f32_e32 v2, 1.0, v2
	v_rcp_f32_e32 v37, v2
	ds_read2st64_b32 v[2:3], v1 offset0:48 offset1:64
	s_waitcnt lgkmcnt(0)
	v_mul_f32_e32 v38, v80, v2
	v_mul_f32_e32 v39, v38, v38
	s_nop 1
	v_mov_b32_dpp v39, v39 quad_perm:[1,0,3,2] row_mask:0xf bank_mask:0xf bound_ctrl:1
	v_fmac_f32_e32 v39, v38, v38
	s_nop 1
	v_add_f32_dpp v39, v39, v39 quad_perm:[2,3,0,1] row_mask:0xf bank_mask:0xf bound_ctrl:1
	s_nop 1
	v_add_f32_dpp v39, v39, v39 row_half_mirror row_mask:0xf bank_mask:0xf bound_ctrl:1
	s_nop 1
	v_add_f32_dpp v39, v39, v39 row_mirror row_mask:0xf bank_mask:0xf bound_ctrl:1
	s_nop 1
	s_nop 0
	v_add_f32_dpp v39, v39, v39 row_bcast:15 row_mask:0xa bank_mask:0xf
	s_nop 0
	s_nop 1
	s_nop 0
	v_add_f32_dpp v39, v39, v39 row_bcast:31 row_mask:0xc bank_mask:0xf
	s_nop 0
	v_readlane_b32 s20, v39, 63
	s_nop 1
	v_add_f32_e32 v39, s20, v184
	v_cmp_gt_f32_e32 vcc, s72, v39
	v_mul_f32_e32 v40, 0x4b800000, v39
	s_nop 0
	v_cndmask_b32_e32 v39, v39, v40, vcc
	v_rsq_f32_e32 v39, v39
	s_nop 0
	v_mul_f32_e32 v40, 0x45800000, v39
	v_cndmask_b32_e32 v39, v39, v40, vcc
	v_mul_f32_e32 v38, v38, v39
	v_add_f32_e32 v39, -1.0, v37
	v_fma_f32 v39, v79, v39, 1.0
	v_mul_f32_e32 v2, v2, v39
	v_mul_f32_e32 v3, v3, v2
	v_mul_f32_e32 v39, v78, v3
	ds_write2st64_b32 v1, v38, v36 offset1:16
	s_nop 0
	v_mov_b32_dpp v39, v39 quad_perm:[1,0,3,2] row_mask:0xf bank_mask:0xf bound_ctrl:1
	v_fmac_f32_e32 v39, v78, v3
	s_nop 1
	v_add_f32_dpp v3, v39, v39 quad_perm:[2,3,0,1] row_mask:0xf bank_mask:0xf bound_ctrl:1
	v_mov_b32_e32 v39, v0
	s_nop 0
	v_add_f32_dpp v3, v3, v3 row_half_mirror row_mask:0xf bank_mask:0xf bound_ctrl:1
	s_nop 1
	v_add_f32_dpp v3, v3, v3 row_mirror row_mask:0xf bank_mask:0xf bound_ctrl:1
	s_nop 1
	s_nop 0
	v_add_f32_dpp v3, v3, v3 row_bcast:15 row_mask:0xa bank_mask:0xf
	s_nop 0
	s_nop 1
	s_nop 0
	v_add_f32_dpp v3, v3, v3 row_bcast:31 row_mask:0xc bank_mask:0xf
	s_nop 0
	v_readlane_b32 s26, v3, 63
	v_mul_f32_e32 v3, v37, v38
	ds_write2st64_b32 v1, v3, v2 offset0:32 offset1:48
	s_and_saveexec_b64 s[20:21], s[16:17]
	v_lshl_add_u32 v1, s22, 2, v145
	v_mov_b32_e32 v2, s26
	ds_write_b32 v1, v2
	s_or_b64 exec, exec, s[20:21]
	v_lshl_add_u32 v1, v88, 2, s23
	ds_read2st64_b32 v[2:3], v1 offset0:16 offset1:32
	v_mov_b32_e32 v40, v0
	s_waitcnt lgkmcnt(0)
	v_add_f32_e32 v2, v82, v2
	v_mul_f32_e32 v2, 0xbfb8aa3b, v2
	v_exp_f32_e32 v2, v2
	v_add_f32_e32 v3, v81, v3
	v_add_f32_e32 v2, 1.0, v2
	v_rcp_f32_e32 v2, v2
	s_nop 0
	v_mul_f32_e32 v2, 0xbf1b4598, v2
	v_mul_f32_e32 v2, 0x3fb8aa3b, v2
	v_exp_f32_e32 v36, v2
	v_mul_f32_e32 v2, 0xbfb8aa3b, v3
	v_exp_f32_e32 v2, v2
	s_nop 0
	v_add_f32_e32 v2, 1.0, v2
	v_rcp_f32_e32 v37, v2
	ds_read2st64_b32 v[2:3], v1 offset0:48 offset1:64
	s_waitcnt lgkmcnt(0)
	v_mul_f32_e32 v38, v80, v2
	v_mul_f32_e32 v39, v38, v38
	s_nop 1
	v_mov_b32_dpp v39, v39 quad_perm:[1,0,3,2] row_mask:0xf bank_mask:0xf bound_ctrl:1
	v_fmac_f32_e32 v39, v38, v38
	s_nop 1
	v_add_f32_dpp v39, v39, v39 quad_perm:[2,3,0,1] row_mask:0xf bank_mask:0xf bound_ctrl:1
	s_nop 1
	v_add_f32_dpp v39, v39, v39 row_half_mirror row_mask:0xf bank_mask:0xf bound_ctrl:1
	s_nop 1
	v_add_f32_dpp v39, v39, v39 row_mirror row_mask:0xf bank_mask:0xf bound_ctrl:1
	s_nop 1
	s_nop 0
	v_add_f32_dpp v39, v39, v39 row_bcast:15 row_mask:0xa bank_mask:0xf
	s_nop 0
	s_nop 1
	s_nop 0
	v_add_f32_dpp v39, v39, v39 row_bcast:31 row_mask:0xc bank_mask:0xf
	s_nop 0
	v_readlane_b32 s20, v39, 63
	s_nop 1
	v_add_f32_e32 v39, s20, v184
	v_cmp_gt_f32_e32 vcc, s72, v39
	v_mul_f32_e32 v40, 0x4b800000, v39
	s_nop 0
	v_cndmask_b32_e32 v39, v39, v40, vcc
	v_rsq_f32_e32 v39, v39
	s_nop 0
	v_mul_f32_e32 v40, 0x45800000, v39
	v_cndmask_b32_e32 v39, v39, v40, vcc
	v_mul_f32_e32 v38, v38, v39
	v_add_f32_e32 v39, -1.0, v37
	v_fma_f32 v39, v79, v39, 1.0
	v_mul_f32_e32 v2, v2, v39
	v_mul_f32_e32 v3, v3, v2
	v_mul_f32_e32 v39, v78, v3
	ds_write2st64_b32 v1, v38, v36 offset1:16
	s_nop 0
	v_mov_b32_dpp v39, v39 quad_perm:[1,0,3,2] row_mask:0xf bank_mask:0xf bound_ctrl:1
	v_fmac_f32_e32 v39, v78, v3
	s_nop 1
	v_add_f32_dpp v3, v39, v39 quad_perm:[2,3,0,1] row_mask:0xf bank_mask:0xf bound_ctrl:1
	v_mov_b32_e32 v39, v0
	s_nop 0
	v_add_f32_dpp v3, v3, v3 row_half_mirror row_mask:0xf bank_mask:0xf bound_ctrl:1
	s_nop 1
	v_add_f32_dpp v3, v3, v3 row_mirror row_mask:0xf bank_mask:0xf bound_ctrl:1
	s_nop 1
	s_nop 0
	v_add_f32_dpp v3, v3, v3 row_bcast:15 row_mask:0xa bank_mask:0xf
	s_nop 0
	s_nop 1
	s_nop 0
	v_add_f32_dpp v3, v3, v3 row_bcast:31 row_mask:0xc bank_mask:0xf
	s_nop 0
	v_readlane_b32 s23, v3, 63
	v_mul_f32_e32 v3, v37, v38
	ds_write2st64_b32 v1, v3, v2 offset0:32 offset1:48
	s_and_saveexec_b64 s[20:21], s[16:17]
	v_lshl_add_u32 v1, s22, 2, v146
	v_mov_b32_e32 v2, s23
	ds_write_b32 v1, v2
	s_or_b64 exec, exec, s[20:21]
